# NSA branch loops: QK K-fragment LDS reads double-buffered (second register quad) so each ds_read overlaps the previous MFMA instead of read-wait-mfma in series
# speedup vs baseline: 1.0240x; 1.0062x over previous
.LBB0_123:
	s_ff1_i32_b32 s14, s12
	v_sub_co_u32_e64 v32, s[94:95], s12, 1
	s_lshl_b32 s15, s14, 6
	s_and_b64 s[78:79], s[94:95], exec
	s_cselect_b32 s15, 0, s15
	v_readfirstlane_b32 s13, v32
	v_add_u32_e32 v32, s15, v231
	v_ashrrev_i32_e32 v33, 31, v32
	s_waitcnt vmcnt(3)
	ds_write_b128 v236, v[80:83] offset:16384
	s_waitcnt vmcnt(2)
	ds_write2_b64 v237, v[84:85], v[86:87] offset1:1
	v_lshlrev_b64 v[32:33], 11, v[32:33]
	s_waitcnt lgkmcnt(0)
	s_barrier
	v_lshl_add_u64 v[32:33], v[152:153], 0, v[32:33]
	s_lshl_b32 s92, s15, 7
	global_load_dwordx4 v[80:83], v[32:33], off
	v_lshl_add_u64 v[32:33], v[154:155], 0, s[92:93]
	global_load_dwordx4 v[84:87], v[32:33], off
	s_lshl_b32 s15, 1, s10
	v_and_b32_e32 v32, s15, v235
	v_cmp_ne_u32_e32 vcc, 0, v32
	s_and_saveexec_b64 s[84:85], vcc
	s_cbranch_execz .LBB0_127
	ds_read_b128 v[244:247], v238 offset:16384
	ds_read_b128 v[248:251], v238 offset:20992
	v_and_b32_e32 v32, s15, v234
	v_cmp_ne_u32_e32 vcc, 0, v32
	s_cmp_lg_u32 s10, s89
	s_cselect_b64 s[78:79], -1, 0
	v_cndmask_b32_e64 v32, v208, -v232, vcc
	v_mov_b32_e32 v33, v32
	v_mov_b32_e32 v34, v32
	v_mov_b32_e32 v35, v32
	v_mov_b32_e32 v36, v32
	v_mov_b32_e32 v37, v32
	v_mov_b32_e32 v38, v32
	v_mov_b32_e32 v39, v32
	v_mov_b32_e32 v40, v32
	v_mov_b32_e32 v41, v32
	v_mov_b32_e32 v42, v32
	v_mov_b32_e32 v43, v32
	v_mov_b32_e32 v44, v32
	v_mov_b32_e32 v45, v32
	v_mov_b32_e32 v46, v32
	v_mov_b32_e32 v47, v32
	s_cmp_lg_u32 s10, s8
	s_cselect_b64 vcc, -1, 0
	s_waitcnt lgkmcnt(1)
	v_mfma_f32_32x32x16_bf16 v[48:63], v[244:247], v[64:67], v[32:47]
	ds_read_b128 v[244:247], v238 offset:16416
	s_and_b64 s[78:79], s[78:79], vcc
	s_and_b64 vcc, exec, s[78:79]
	s_waitcnt lgkmcnt(1)
	v_mfma_f32_32x32x16_bf16 v[32:47], v[248:251], v[64:67], v[32:47]
	ds_read_b128 v[248:251], v238 offset:21024
	s_waitcnt lgkmcnt(1)
	v_mfma_f32_32x32x16_bf16 v[48:63], v[244:247], v[68:71], v[48:63]
	ds_read_b128 v[244:247], v238 offset:16448
	s_waitcnt lgkmcnt(1)
	v_mfma_f32_32x32x16_bf16 v[32:47], v[248:251], v[68:71], v[32:47]
	ds_read_b128 v[248:251], v238 offset:21056
	s_waitcnt lgkmcnt(1)
	v_mfma_f32_32x32x16_bf16 v[48:63], v[244:247], v[72:75], v[48:63]
	ds_read_b128 v[244:247], v238 offset:16480
	s_waitcnt lgkmcnt(1)
	v_mfma_f32_32x32x16_bf16 v[32:47], v[248:251], v[72:75], v[32:47]
	ds_read_b128 v[248:251], v238 offset:21088
	s_waitcnt lgkmcnt(1)
	v_mfma_f32_32x32x16_bf16 v[48:63], v[244:247], v[76:79], v[48:63]
	s_waitcnt lgkmcnt(0)
	v_mfma_f32_32x32x16_bf16 v[32:47], v[248:251], v[76:79], v[32:47]
	s_cbranch_vccnz .LBB0_126
	v_lshl_or_b32 v156, s10, 6, v102
	v_cmp_lt_i32_e32 vcc, v156, v233
	v_cmp_gt_i32_e64 s[78:79], v156, v117
	s_or_b64 vcc, vcc, s[78:79]
	v_or_b32_e32 v157, 32, v156
	s_nop 2
	v_cndmask_b32_e32 v48, v48, v208, vcc
	v_cmp_lt_i32_e32 vcc, v157, v233
	v_cmp_gt_i32_e64 s[78:79], v157, v117
	s_or_b64 vcc, vcc, s[78:79]
	v_or_b32_e32 v157, 1, v156
	v_cndmask_b32_e32 v32, v32, v208, vcc
	v_cmp_lt_i32_e32 vcc, v157, v233
	v_cmp_ge_i32_e64 s[78:79], v156, v117
	s_or_b64 vcc, s[78:79], vcc
	v_or_b32_e32 v157, 33, v156
	v_cndmask_b32_e32 v49, v49, v208, vcc
	v_cmp_lt_i32_e32 vcc, v157, v233
	v_cmp_gt_i32_e64 s[78:79], v157, v117
	s_or_b64 vcc, vcc, s[78:79]
	v_or_b32_e32 v157, 2, v156
	v_cndmask_b32_e32 v33, v33, v208, vcc
	v_cmp_lt_i32_e32 vcc, v157, v233
	v_cmp_gt_i32_e64 s[78:79], v157, v117
	s_or_b64 vcc, vcc, s[78:79]
	v_or_b32_e32 v157, 34, v156
	v_cndmask_b32_e32 v50, v50, v208, vcc
	v_cmp_lt_i32_e32 vcc, v157, v233
	v_cmp_gt_i32_e64 s[78:79], v157, v117
	s_or_b64 vcc, vcc, s[78:79]
	v_or_b32_e32 v157, 3, v156
	v_cndmask_b32_e32 v34, v34, v208, vcc
	v_cmp_lt_i32_e32 vcc, v157, v233
	v_cmp_gt_i32_e64 s[78:79], v157, v117
	s_or_b64 vcc, vcc, s[78:79]
	v_or_b32_e32 v157, 35, v156
	v_cndmask_b32_e32 v51, v51, v208, vcc
	v_cmp_lt_i32_e32 vcc, v157, v233
	v_cmp_gt_i32_e64 s[78:79], v157, v117
	s_or_b64 vcc, vcc, s[78:79]
	v_or_b32_e32 v157, 8, v156
	v_cndmask_b32_e32 v35, v35, v208, vcc
	v_cmp_lt_i32_e32 vcc, v157, v233
	v_cmp_gt_i32_e64 s[78:79], v157, v117
	s_or_b64 vcc, vcc, s[78:79]
	v_or_b32_e32 v157, 40, v156
	v_cndmask_b32_e32 v52, v52, v208, vcc
	v_cmp_lt_i32_e32 vcc, v157, v233
	v_cmp_gt_i32_e64 s[78:79], v157, v117
	s_or_b64 vcc, vcc, s[78:79]
	v_or_b32_e32 v157, 9, v156
	v_cndmask_b32_e32 v36, v36, v208, vcc
	v_cmp_lt_i32_e32 vcc, v157, v233
	v_cmp_gt_i32_e64 s[78:79], v157, v117
	s_or_b64 vcc, vcc, s[78:79]
	v_or_b32_e32 v157, 41, v156
	v_cndmask_b32_e32 v53, v53, v208, vcc
	v_cmp_lt_i32_e32 vcc, v157, v233
	v_cmp_gt_i32_e64 s[78:79], v157, v117
	s_or_b64 vcc, vcc, s[78:79]
	v_or_b32_e32 v157, 10, v156
	v_cndmask_b32_e32 v37, v37, v208, vcc
	v_cmp_lt_i32_e32 vcc, v157, v233
	v_cmp_gt_i32_e64 s[78:79], v157, v117
	s_or_b64 vcc, vcc, s[78:79]
	v_or_b32_e32 v157, 42, v156
	v_cndmask_b32_e32 v54, v54, v208, vcc
	v_cmp_lt_i32_e32 vcc, v157, v233
	v_cmp_gt_i32_e64 s[78:79], v157, v117
	s_or_b64 vcc, vcc, s[78:79]
	v_or_b32_e32 v157, 11, v156
	v_cndmask_b32_e32 v38, v38, v208, vcc
	v_cmp_lt_i32_e32 vcc, v157, v233
	v_cmp_gt_i32_e64 s[78:79], v157, v117
	s_or_b64 vcc, vcc, s[78:79]
	v_or_b32_e32 v157, 43, v156
	v_cndmask_b32_e32 v55, v55, v208, vcc
	v_cmp_lt_i32_e32 vcc, v157, v233
	v_cmp_gt_i32_e64 s[78:79], v157, v117
	s_or_b64 vcc, vcc, s[78:79]
	v_or_b32_e32 v157, 16, v156
	v_cndmask_b32_e32 v39, v39, v208, vcc
	v_cmp_lt_i32_e32 vcc, v157, v233
	v_cmp_gt_i32_e64 s[78:79], v157, v117
	s_or_b64 vcc, vcc, s[78:79]
	v_or_b32_e32 v157, 48, v156
	v_cndmask_b32_e32 v56, v56, v208, vcc
	v_cmp_lt_i32_e32 vcc, v157, v233
	v_cmp_gt_i32_e64 s[78:79], v157, v117
	s_or_b64 vcc, vcc, s[78:79]
	v_or_b32_e32 v157, 17, v156
	v_cndmask_b32_e32 v40, v40, v208, vcc
	v_cmp_lt_i32_e32 vcc, v157, v233
	v_cmp_gt_i32_e64 s[78:79], v157, v117
	s_or_b64 vcc, vcc, s[78:79]
	v_or_b32_e32 v157, 49, v156
	v_cndmask_b32_e32 v57, v57, v208, vcc
	v_cmp_lt_i32_e32 vcc, v157, v233
	v_cmp_gt_i32_e64 s[78:79], v157, v117
	s_or_b64 vcc, vcc, s[78:79]
	v_or_b32_e32 v157, 18, v156
	v_cndmask_b32_e32 v41, v41, v208, vcc
	v_cmp_lt_i32_e32 vcc, v157, v233
	v_cmp_gt_i32_e64 s[78:79], v157, v117
	s_or_b64 vcc, vcc, s[78:79]
	v_or_b32_e32 v157, 50, v156
	v_cndmask_b32_e32 v58, v58, v208, vcc
	v_cmp_lt_i32_e32 vcc, v157, v233
	v_cmp_gt_i32_e64 s[78:79], v157, v117
	s_or_b64 vcc, vcc, s[78:79]
	v_or_b32_e32 v157, 19, v156
	v_cndmask_b32_e32 v42, v42, v208, vcc
	v_cmp_lt_i32_e32 vcc, v157, v233
	v_cmp_gt_i32_e64 s[78:79], v157, v117
	s_or_b64 vcc, vcc, s[78:79]
	v_or_b32_e32 v157, 51, v156
	v_cndmask_b32_e32 v59, v59, v208, vcc
	v_cmp_lt_i32_e32 vcc, v157, v233
	v_cmp_gt_i32_e64 s[78:79], v157, v117
	s_or_b64 vcc, vcc, s[78:79]
	v_or_b32_e32 v157, 24, v156
	v_cndmask_b32_e32 v43, v43, v208, vcc
	v_cmp_lt_i32_e32 vcc, v157, v233
	v_cmp_gt_i32_e64 s[78:79], v157, v117
	s_or_b64 vcc, vcc, s[78:79]
	v_or_b32_e32 v157, 56, v156
	v_cndmask_b32_e32 v60, v60, v208, vcc
	v_cmp_lt_i32_e32 vcc, v157, v233
	v_cmp_gt_i32_e64 s[78:79], v157, v117
	s_or_b64 vcc, vcc, s[78:79]
	v_or_b32_e32 v157, 25, v156
	v_cndmask_b32_e32 v44, v44, v208, vcc
	v_cmp_lt_i32_e32 vcc, v157, v233
	v_cmp_gt_i32_e64 s[78:79], v157, v117
	s_or_b64 vcc, vcc, s[78:79]
	v_or_b32_e32 v157, 57, v156
	v_cndmask_b32_e32 v61, v61, v208, vcc
	v_cmp_lt_i32_e32 vcc, v157, v233
	v_cmp_gt_i32_e64 s[78:79], v157, v117
	s_or_b64 vcc, vcc, s[78:79]
	v_or_b32_e32 v157, 26, v156
	v_cndmask_b32_e32 v45, v45, v208, vcc
	v_cmp_lt_i32_e32 vcc, v157, v233
	v_cmp_gt_i32_e64 s[78:79], v157, v117
	s_or_b64 vcc, vcc, s[78:79]
	v_or_b32_e32 v157, 58, v156
	v_cndmask_b32_e32 v62, v62, v208, vcc
	v_cmp_lt_i32_e32 vcc, v157, v233
	v_cmp_gt_i32_e64 s[78:79], v157, v117
	s_or_b64 vcc, vcc, s[78:79]
	v_or_b32_e32 v157, 27, v156
	v_cndmask_b32_e32 v46, v46, v208, vcc
	v_cmp_lt_i32_e32 vcc, v157, v233
	v_cmp_gt_i32_e64 s[78:79], v157, v117
	s_or_b64 vcc, vcc, s[78:79]
	v_or_b32_e32 v156, 59, v156
	v_cndmask_b32_e32 v63, v63, v208, vcc
	v_cmp_lt_i32_e32 vcc, v156, v233
	v_cmp_gt_i32_e64 s[78:79], v156, v117
	s_or_b64 vcc, vcc, s[78:79]
	v_cndmask_b32_e32 v47, v47, v208, vcc

.LBB0_127:
	s_or_b64 exec, exec, s[84:85]
	s_cmp_lt_i32 s11, 0
	s_cbranch_scc1 .LBB0_131
	s_and_b32 s12, s13, s12
	v_sub_co_u32_e64 v36, s[78:79], s12, 1
	s_ff1_i32_b32 s10, s12
	s_and_b64 s[78:79], s[78:79], exec
	s_cselect_b32 s13, -1, s10
	s_max_i32 s10, s13, 0
	v_lshl_add_u32 v32, s10, 6, v231
	v_ashrrev_i32_e32 v33, 31, v32
	s_waitcnt vmcnt(2)
	ds_write_b128 v240, v[88:91] offset:16384
	ds_write2_b64 v241, v[92:93], v[94:95] offset1:1
	v_lshlrev_b64 v[32:33], 11, v[32:33]
	s_waitcnt lgkmcnt(0)
	s_barrier
	v_lshl_add_u64 v[32:33], v[152:153], 0, v[32:33]
	s_lshl_b32 s92, s10, 13
	v_lshl_add_u64 v[34:35], v[154:155], 0, s[92:93]
	global_load_dwordx4 v[88:91], v[32:33], off
	global_load_dwordx4 v[92:95], v[34:35], off
	s_lshl_b32 s10, 1, s11
	v_and_b32_e32 v32, s10, v235
	v_readfirstlane_b32 s92, v36
	v_cmp_ne_u32_e32 vcc, 0, v32
	s_and_saveexec_b64 s[84:85], vcc
	s_cbranch_execz .LBB0_122
	ds_read_b128 v[244:247], v242 offset:16384
	ds_read_b128 v[248:251], v242 offset:20992
	v_and_b32_e32 v32, s10, v234
	v_cmp_ne_u32_e32 vcc, 0, v32
	s_cmp_lg_u32 s11, s89
	s_cselect_b64 s[78:79], -1, 0
	v_cndmask_b32_e64 v32, v208, -v232, vcc
	v_mov_b32_e32 v33, v32
	v_mov_b32_e32 v34, v32
	v_mov_b32_e32 v35, v32
	v_mov_b32_e32 v36, v32
	v_mov_b32_e32 v37, v32
	v_mov_b32_e32 v38, v32
	v_mov_b32_e32 v39, v32
	v_mov_b32_e32 v40, v32
	v_mov_b32_e32 v41, v32
	v_mov_b32_e32 v42, v32
	v_mov_b32_e32 v43, v32
	v_mov_b32_e32 v44, v32
	v_mov_b32_e32 v45, v32
	v_mov_b32_e32 v46, v32
	v_mov_b32_e32 v47, v32
	s_cmp_lg_u32 s11, s8
	s_cselect_b64 vcc, -1, 0
	s_waitcnt lgkmcnt(1)
	v_mfma_f32_32x32x16_bf16 v[48:63], v[244:247], v[64:67], v[32:47]
	ds_read_b128 v[244:247], v242 offset:16416
	s_and_b64 s[78:79], s[78:79], vcc
	s_and_b64 vcc, exec, s[78:79]
	s_waitcnt lgkmcnt(1)
	v_mfma_f32_32x32x16_bf16 v[32:47], v[248:251], v[64:67], v[32:47]
	ds_read_b128 v[248:251], v242 offset:21024
	s_waitcnt lgkmcnt(1)
	v_mfma_f32_32x32x16_bf16 v[48:63], v[244:247], v[68:71], v[48:63]
	ds_read_b128 v[244:247], v242 offset:16448
	s_waitcnt lgkmcnt(1)
	v_mfma_f32_32x32x16_bf16 v[32:47], v[248:251], v[68:71], v[32:47]
	ds_read_b128 v[248:251], v242 offset:21056
	s_waitcnt lgkmcnt(1)
	v_mfma_f32_32x32x16_bf16 v[48:63], v[244:247], v[72:75], v[48:63]
	ds_read_b128 v[244:247], v242 offset:16480
	s_waitcnt lgkmcnt(1)
	v_mfma_f32_32x32x16_bf16 v[32:47], v[248:251], v[72:75], v[32:47]
	ds_read_b128 v[248:251], v242 offset:21088
	s_waitcnt lgkmcnt(1)
	v_mfma_f32_32x32x16_bf16 v[48:63], v[244:247], v[76:79], v[48:63]
	s_waitcnt lgkmcnt(0)
	v_mfma_f32_32x32x16_bf16 v[32:47], v[248:251], v[76:79], v[32:47]
	s_cbranch_vccnz .LBB0_121
	v_lshl_or_b32 v156, s11, 6, v102
	v_cmp_lt_i32_e32 vcc, v156, v233
	v_cmp_gt_i32_e64 s[78:79], v156, v117
	s_or_b64 vcc, vcc, s[78:79]
	v_or_b32_e32 v157, 32, v156
	s_nop 2
	v_cndmask_b32_e32 v48, v48, v208, vcc
	v_cmp_lt_i32_e32 vcc, v157, v233
	v_cmp_gt_i32_e64 s[78:79], v157, v117
	s_or_b64 vcc, vcc, s[78:79]
	v_or_b32_e32 v157, 1, v156
	v_cndmask_b32_e32 v32, v32, v208, vcc
	v_cmp_lt_i32_e32 vcc, v157, v233
	v_cmp_ge_i32_e64 s[78:79], v156, v117
	s_or_b64 vcc, s[78:79], vcc
	v_or_b32_e32 v157, 33, v156
	v_cndmask_b32_e32 v49, v49, v208, vcc
	v_cmp_lt_i32_e32 vcc, v157, v233
	v_cmp_gt_i32_e64 s[78:79], v157, v117
	s_or_b64 vcc, vcc, s[78:79]
	v_or_b32_e32 v157, 2, v156
	v_cndmask_b32_e32 v33, v33, v208, vcc
	v_cmp_lt_i32_e32 vcc, v157, v233
	v_cmp_gt_i32_e64 s[78:79], v157, v117
	s_or_b64 vcc, vcc, s[78:79]
	v_or_b32_e32 v157, 34, v156
	v_cndmask_b32_e32 v50, v50, v208, vcc
	v_cmp_lt_i32_e32 vcc, v157, v233
	v_cmp_gt_i32_e64 s[78:79], v157, v117
	s_or_b64 vcc, vcc, s[78:79]
	v_or_b32_e32 v157, 3, v156
	v_cndmask_b32_e32 v34, v34, v208, vcc
	v_cmp_lt_i32_e32 vcc, v157, v233
	v_cmp_gt_i32_e64 s[78:79], v157, v117
	s_or_b64 vcc, vcc, s[78:79]
	v_or_b32_e32 v157, 35, v156
	v_cndmask_b32_e32 v51, v51, v208, vcc
	v_cmp_lt_i32_e32 vcc, v157, v233
	v_cmp_gt_i32_e64 s[78:79], v157, v117
	s_or_b64 vcc, vcc, s[78:79]
	v_or_b32_e32 v157, 8, v156
	v_cndmask_b32_e32 v35, v35, v208, vcc
	v_cmp_lt_i32_e32 vcc, v157, v233
	v_cmp_gt_i32_e64 s[78:79], v157, v117
	s_or_b64 vcc, vcc, s[78:79]
	v_or_b32_e32 v157, 40, v156
	v_cndmask_b32_e32 v52, v52, v208, vcc
	v_cmp_lt_i32_e32 vcc, v157, v233
	v_cmp_gt_i32_e64 s[78:79], v157, v117
	s_or_b64 vcc, vcc, s[78:79]
	v_or_b32_e32 v157, 9, v156
	v_cndmask_b32_e32 v36, v36, v208, vcc
	v_cmp_lt_i32_e32 vcc, v157, v233
	v_cmp_gt_i32_e64 s[78:79], v157, v117
	s_or_b64 vcc, vcc, s[78:79]
	v_or_b32_e32 v157, 41, v156
	v_cndmask_b32_e32 v53, v53, v208, vcc
	v_cmp_lt_i32_e32 vcc, v157, v233
	v_cmp_gt_i32_e64 s[78:79], v157, v117
	s_or_b64 vcc, vcc, s[78:79]
	v_or_b32_e32 v157, 10, v156
	v_cndmask_b32_e32 v37, v37, v208, vcc
	v_cmp_lt_i32_e32 vcc, v157, v233
	v_cmp_gt_i32_e64 s[78:79], v157, v117
	s_or_b64 vcc, vcc, s[78:79]
	v_or_b32_e32 v157, 42, v156
	v_cndmask_b32_e32 v54, v54, v208, vcc
	v_cmp_lt_i32_e32 vcc, v157, v233
	v_cmp_gt_i32_e64 s[78:79], v157, v117
	s_or_b64 vcc, vcc, s[78:79]
	v_or_b32_e32 v157, 11, v156
	v_cndmask_b32_e32 v38, v38, v208, vcc
	v_cmp_lt_i32_e32 vcc, v157, v233
	v_cmp_gt_i32_e64 s[78:79], v157, v117
	s_or_b64 vcc, vcc, s[78:79]
	v_or_b32_e32 v157, 43, v156
	v_cndmask_b32_e32 v55, v55, v208, vcc
	v_cmp_lt_i32_e32 vcc, v157, v233
	v_cmp_gt_i32_e64 s[78:79], v157, v117
	s_or_b64 vcc, vcc, s[78:79]
	v_or_b32_e32 v157, 16, v156
	v_cndmask_b32_e32 v39, v39, v208, vcc
	v_cmp_lt_i32_e32 vcc, v157, v233
	v_cmp_gt_i32_e64 s[78:79], v157, v117
	s_or_b64 vcc, vcc, s[78:79]
	v_or_b32_e32 v157, 48, v156
	v_cndmask_b32_e32 v56, v56, v208, vcc
	v_cmp_lt_i32_e32 vcc, v157, v233
	v_cmp_gt_i32_e64 s[78:79], v157, v117
	s_or_b64 vcc, vcc, s[78:79]
	v_or_b32_e32 v157, 17, v156
	v_cndmask_b32_e32 v40, v40, v208, vcc
	v_cmp_lt_i32_e32 vcc, v157, v233
	v_cmp_gt_i32_e64 s[78:79], v157, v117
	s_or_b64 vcc, vcc, s[78:79]
	v_or_b32_e32 v157, 49, v156
	v_cndmask_b32_e32 v57, v57, v208, vcc
	v_cmp_lt_i32_e32 vcc, v157, v233
	v_cmp_gt_i32_e64 s[78:79], v157, v117
	s_or_b64 vcc, vcc, s[78:79]
	v_or_b32_e32 v157, 18, v156
	v_cndmask_b32_e32 v41, v41, v208, vcc
	v_cmp_lt_i32_e32 vcc, v157, v233
	v_cmp_gt_i32_e64 s[78:79], v157, v117
	s_or_b64 vcc, vcc, s[78:79]
	v_or_b32_e32 v157, 50, v156
	v_cndmask_b32_e32 v58, v58, v208, vcc
	v_cmp_lt_i32_e32 vcc, v157, v233
	v_cmp_gt_i32_e64 s[78:79], v157, v117
	s_or_b64 vcc, vcc, s[78:79]
	v_or_b32_e32 v157, 19, v156
	v_cndmask_b32_e32 v42, v42, v208, vcc
	v_cmp_lt_i32_e32 vcc, v157, v233
	v_cmp_gt_i32_e64 s[78:79], v157, v117
	s_or_b64 vcc, vcc, s[78:79]
	v_or_b32_e32 v157, 51, v156
	v_cndmask_b32_e32 v59, v59, v208, vcc
	v_cmp_lt_i32_e32 vcc, v157, v233
	v_cmp_gt_i32_e64 s[78:79], v157, v117
	s_or_b64 vcc, vcc, s[78:79]
	v_or_b32_e32 v157, 24, v156
	v_cndmask_b32_e32 v43, v43, v208, vcc
	v_cmp_lt_i32_e32 vcc, v157, v233
	v_cmp_gt_i32_e64 s[78:79], v157, v117
	s_or_b64 vcc, vcc, s[78:79]
	v_or_b32_e32 v157, 56, v156
	v_cndmask_b32_e32 v60, v60, v208, vcc
	v_cmp_lt_i32_e32 vcc, v157, v233
	v_cmp_gt_i32_e64 s[78:79], v157, v117
	s_or_b64 vcc, vcc, s[78:79]
	v_or_b32_e32 v157, 25, v156
	v_cndmask_b32_e32 v44, v44, v208, vcc
	v_cmp_lt_i32_e32 vcc, v157, v233
	v_cmp_gt_i32_e64 s[78:79], v157, v117
	s_or_b64 vcc, vcc, s[78:79]
	v_or_b32_e32 v157, 57, v156
	v_cndmask_b32_e32 v61, v61, v208, vcc
	v_cmp_lt_i32_e32 vcc, v157, v233
	v_cmp_gt_i32_e64 s[78:79], v157, v117
	s_or_b64 vcc, vcc, s[78:79]
	v_or_b32_e32 v157, 26, v156
	v_cndmask_b32_e32 v45, v45, v208, vcc
	v_cmp_lt_i32_e32 vcc, v157, v233
	v_cmp_gt_i32_e64 s[78:79], v157, v117
	s_or_b64 vcc, vcc, s[78:79]
	v_or_b32_e32 v157, 58, v156
	v_cndmask_b32_e32 v62, v62, v208, vcc
	v_cmp_lt_i32_e32 vcc, v157, v233
	v_cmp_gt_i32_e64 s[78:79], v157, v117
	s_or_b64 vcc, vcc, s[78:79]
	v_or_b32_e32 v157, 27, v156
	v_cndmask_b32_e32 v46, v46, v208, vcc
	v_cmp_lt_i32_e32 vcc, v157, v233
	v_cmp_gt_i32_e64 s[78:79], v157, v117
	s_or_b64 vcc, vcc, s[78:79]
	v_or_b32_e32 v156, 59, v156
	v_cndmask_b32_e32 v63, v63, v208, vcc
	v_cmp_lt_i32_e32 vcc, v156, v233
	v_cmp_gt_i32_e64 s[78:79], v156, v117
	s_or_b64 vcc, vcc, s[78:79]
	v_cndmask_b32_e32 v47, v47, v208, vcc
	s_branch .LBB0_121
